# speedup vs baseline: 1.0025x; 1.0025x over previous
; __device__ __forceinline__ void merge_phase(const bh* __restrict__ ys, const bh* __restrict__ G, const bh* __restrict__ Wb,
;                             const float* __restrict__ ssp, bh* __restrict__ merged, char* lds) {
;     ...
;       for (int hf = 0; hf < 2; ++hf) {
; #pragma unroll
;         for (int i = 0; i < 4; ++i) {
;           const int id = tid + 512 * (hf * 4 + i), r = id >> 4, c8 = (id & 15) * 8;
;           *reinterpret_cast<bf16x8*>(gs + r * 136 + c8) =
;               *reinterpret_cast<const bf16x8*>(G + (long)(tm * 256 + r) * 4096 + n * 1024 + tn * 128 + c8);
;         }
;         asm volatile("" ::: "memory");
;       }
;       if (tid < 256) {
;         float scv = 1.f;
;         if (n == 2) { const int row = tm * 256 + tid; scv = rsqrtf((ssp[row * 2] + ssp[row * 2 + 1]) * (1.f / 512.f) + EPS); }
;         scs[tid] = scv;
;       }
.Lmy_merge_pref:
	v_lshl_add_u64 v[86:87], s[48:49], 1, v[138:139]
	v_lshl_add_u64 v[64:65], v[86:87], 0, v[144:145]
	global_load_dwordx4 v[64:67], v[64:65], off
	v_lshl_add_u64 v[68:69], v[86:87], 0, v[148:149]
	global_load_dwordx4 v[68:71], v[68:69], off
	v_lshl_add_u64 v[72:73], v[86:87], 0, v[150:151]
	global_load_dwordx4 v[72:75], v[72:73], off
	v_lshl_add_u64 v[76:77], v[86:87], 0, v[152:153]
	global_load_dwordx4 v[76:79], v[76:77], off
	v_lshl_add_u64 v[80:81], v[86:87], 0, v[154:155]
	global_load_dwordx4 v[80:83], v[80:81], off
	v_lshl_add_u64 v[84:85], v[86:87], 0, v[158:159]
	global_load_dwordx4 v[84:87], v[84:85], off
	s_branch .LBB0_798
.LBB0_800:
	v_lshl_add_u64 v[228:229], s[48:49], 1, v[138:139]
	v_lshl_add_u64 v[230:231], v[228:229], 0, v[162:163]
	global_load_dwordx4 v[232:235], v[230:231], off
	v_lshl_add_u64 v[230:231], v[228:229], 0, v[164:165]
	global_load_dwordx4 v[236:239], v[230:231], off
	s_waitcnt vmcnt(2)
	ds_write_b128 v214, v[64:67]
	ds_write_b128 v215, v[68:71]
	ds_write_b128 v216, v[72:75]
	ds_write_b128 v217, v[76:79]
	ds_write_b128 v218, v[80:83]
	ds_write_b128 v219, v[84:87]
	s_waitcnt vmcnt(1)
	ds_write_b128 v220, v[232:235]
	s_waitcnt vmcnt(0)
	ds_write_b128 v221, v[236:239]
	s_and_saveexec_b64 s[8:9], s[0:1]
	s_cbranch_execz .LBB0_793
	s_cmp_lg_u32 s20, 2
	v_mov_b32_e32 v64, 1.0
	s_cbranch_scc1 .LBB0_792
	global_load_dwordx2 v[64:65], v[142:143], off
	s_waitcnt vmcnt(0)
	v_add_f32_e32 v64, v64, v65
	v_fmamk_f32 v64, v64, 0x3b000000, v189
	v_mul_f32_e32 v65, 0x4b800000, v64
	v_cmp_gt_f32_e32 vcc, s46, v64
	s_nop 1
	v_cndmask_b32_e32 v64, v64, v65, vcc
	v_rsq_f32_e32 v64, v64
	s_nop 0
	v_mul_f32_e32 v65, 0x45800000, v64
	v_cndmask_b32_e32 v64, v64, v65, vcc
	s_branch .LBB0_792
